# v28 (no per-block s_setprio flips) + one static s_setprio 1 for waves 4-7 at kernel start
# baseline (speedup 1.0000x reference)
; #define LAS __attribute__((address_space(3)))
; __device__ __forceinline__ void transpose_item64(const float* W, int Nsrc, int mode, bf16_t* WT, int ldwt, int koff, int nblk, LAS float* scr, int item, int lane) {
;   const int kb = item / nblk, nb = item % nblk, k0 = 64 * kb, n0 = 64 * nb;
;   const int kr = lane >> 4, nq = (lane & 15) * 4;
;   const int sc = src_col(mode, n0 + nq);
;   const float* wp = W + (size_t)(k0 + kr) * Nsrc + (sc >= 0 ? sc : 0);
; __global__ void __launch_bounds__(512, 2) mega_fwd(Args a) {
;     ...
;   const int tid = threadIdx.x, lane = tid & 63, wave = __builtin_amdgcn_readfirstlane(tid >> 6);
;   const int G = gridDim.x, bx = blockIdx.x;
;   const int gw = bx * 8 + wave, NGW = G * 8;
;     ...
;   if (IN(0)) _Pragma("nounroll") for (int rep_ = 0; rep_ < REPS(0); ++rep_) {
;     LAS float* scr = (LAS float*)(ldsl + wave * 16896);
;     constexpr int I_IN = 32 * 164;
;     for (int it = gw; it < I_IN; it += NGW) transpose_item64(a.in[10], NIN, 1, WT_IN, 2048, 0, 164, scr, it, lane);
.LBB0_5:
	s_or_b64 exec, exec, s[2:3]
	s_lshr_b32 s3, s6, 6
	s_lshl_b32 s2, s68, 3
	s_add_i32 s96, s3, s2
	s_lshl_b32 s78, s82, 3
	s_cmp_lt_u32 s3, 4
	s_cbranch_scc1 .Lprio_static_skip
	s_setprio 1
.Lprio_static_skip:
	s_add_u32 s2, s84, 0x9900000
	v_writelane_b32 v251, s3, 21
	s_addc_u32 s3, s85, 0
	v_writelane_b32 v251, s2, 22
	s_load_dwordx16 s[40:55], s[0:1], 0x40
	v_and_b32_e32 v195, 63, v1
	v_writelane_b32 v251, s3, 23
	s_add_u32 s2, s84, 0x225c0000
	s_addc_u32 s3, s85, 0
	v_writelane_b32 v251, s2, 24
	s_cmp_lt_i32 s86, 1
	s_nop 0
	v_writelane_b32 v251, s3, 25
	s_cselect_b64 s[2:3], -1, 0
	s_cmp_gt_i32 s87, 0
	v_writelane_b32 v251, s84, 26
	s_cselect_b64 s[4:5], -1, 0
	s_and_b64 s[2:3], s[2:3], s[4:5]
	v_writelane_b32 v251, s85, 27
	v_writelane_b32 v251, s86, 28
	v_writelane_b32 v251, s87, 29
	s_andn2_b64 vcc, exec, s[2:3]
	v_writelane_b32 v251, s82, 30
	s_nop 1
	v_writelane_b32 v251, s83, 31
	s_cbranch_vccnz .LBB0_24
	s_cmpk_gt_i32 s96, 0x147f
	s_cbranch_scc1 .LBB0_16
	v_readlane_b32 s4, v251, 21
	s_mulk_i32 s4, 0x4200
	v_lshlrev_b32_e32 v2, 2, v1
	v_lshlrev_b32_e32 v4, 3, v1
	s_add_i32 s4, s4, 0
	v_lshrrev_b32_e32 v70, 4, v195
	v_and_b32_e32 v71, 60, v2
	v_lshrrev_b32_e32 v72, 3, v195
	v_and_b32_e32 v4, 56, v4
	v_lshl_add_u32 v2, v71, 2, s4
	v_mul_u32_u24_e32 v3, 0x104, v70
	v_mul_u32_u24_e32 v5, 0x104, v4
	v_lshlrev_b32_e32 v66, 1, v4
	v_mov_b32_e32 v67, 0
	v_lshlrev_b32_e32 v4, 2, v72
	v_lshl_add_u64 v[68:69], s[84:85], 0, v[66:67]
	v_add3_u32 v73, s4, v5, v4
	s_lshl_b32 s8, s96, 6
	s_lshl_b32 s9, s78, 6
	s_movk_i32 s10, 0x17ff
	s_movk_i32 s11, 0x2808
	s_mov_b32 s12, 0xa020
	v_add_u32_e32 v74, v2, v3
	s_mov_b32 s13, s96
	s_branch .LBB0_9
